# v22 plus 14 dedicated converter workgroups in FFN2-gu only (tiles strided by 242)
# speedup vs baseline: 1.0016x; 1.0016x over previous
.LBB0_2294:
	s_or_b64 exec, exec, s[0:1]
	v_readlane_b32 s0, v234, 14
	v_mov_b32_e32 v8, v183
	s_cmpk_lt_i32 s0, 0xf2
	s_cselect_b64 s[0:1], -1, 0
	s_waitcnt lgkmcnt(0)
	s_barrier
	s_andn2_b64 vcc, exec, s[0:1]
	v_readfirstlane_b32 s7, v8
	s_cbranch_vccnz .LBB0_2318
	v_readlane_b32 s1, v234, 14
	s_ashr_i32 s26, s1, 31
	s_lshr_b32 s0, s26, 29
	s_add_i32 s3, s1, s0
	s_and_b32 s0, s3, -8
	s_sub_i32 s6, s1, s0
	s_cmp_gt_i32 s6, 3
	s_cbranch_scc0 .LBB0_2297
	s_mul_i32 s0, s6, 0xb5
	s_add_i32 s2, s0, 4
	s_cbranch_execz .LBB0_2298
	s_branch .LBB0_2299
